# split-K G9 tail as v30 but partials moved as 16-byte write-through stores / 16-byte loads over register quads
# speedup vs baseline: 1.0134x; 1.0036x over previous
; #define PG8_STAGE(bufoff, gbase, voff) do { _Pragma("unroll") for (int _i = 0; _i < 2; ++_i) \
;         __builtin_amdgcn_global_load_lds((const unsigned*)((const char*)(gbase) + (voff)[_i]), (LAS unsigned*)(lds + (bufoff) + ldsw + _i * 8192), 16, 0, 0); } while (0)
; #define PG8_LDA(dst, b, h) do { _Pragma("unroll") for (int m = 0; m < 4; ++m) _Pragma("unroll") for (int k = 0; k < 2; ++k) dst[m][k] = *(const LAS bf16x8*)(lds + PG8_SA(b, h) + aoff + m * 2048 + k * 1024); } while (0)
; #define PG8_LDB(dst, b, h) do { _Pragma("unroll") for (int n = 0; n < 2; ++n) _Pragma("unroll") for (int k = 0; k < 2; ++k) dst[n][k] = *(const LAS bf16x8*)(lds + PG8_SB(b, h) + boff + n * 2048 + k * 1024); } while (0)
; #define PG8_MMA(ai, bj, At, Bt) do { __builtin_amdgcn_s_setprio(1); _Pragma("unroll") for (int m = 0; m < 4; ++m) _Pragma("unroll") for (int n = 0; n < 2; ++n) _Pragma("unroll") for (int k = 0; k < 2; ++k) \
;         acc[ai][bj][m][n] = __builtin_amdgcn_mfma_f32_16x16x32_bf16(Bt[n][k], At[m][k], acc[ai][bj][m][n], 0, 0, 0); __builtin_amdgcn_s_setprio(0); } while (0)
; #define PG8_WAIT_L(n) asm volatile("s_waitcnt lgkmcnt(" #n ")" ::: "memory")
; #define PG8_BAR __builtin_amdgcn_s_barrier()
; #define PG8_SCHED __builtin_amdgcn_sched_barrier(0)
; template <class Epi, class SchedT>
; DI void gemm_phase(LAS unsigned char* lds, const Gemm g, const SchedT& S, const Epi& E) {
;     ...
;             PG8_LDB(B0, 0, 0); PG8_SCHED; PG8_LDA(At, 0, 0); PG8_STAGE(PG8_SA(1, 1), a1 + hstepA, voffA);
;             PG8_WAIT_L(8); PG8_BAR; PG8_WAIT_L(0); PG8_MMA(0, 0, At, B0); PG8_BAR; PG8_SCHED;
;             PG8_LDB(B1, 0, 1); PG8_STAGE(PG8_SB(0, 0), b2, voffB);
;             PG8_BAR; PG8_WAIT_L(0); PG8_MMA(0, 1, At, B1); PG8_BAR;
;             PG8_LDA(At, 0, 1); PG8_STAGE(PG8_SA(0, 0), a2, voffA);
;             PG8_BAR; PG8_WAIT_L(0); PG8_MMA(1, 0, At, B0); PG8_BAR; PG8_SCHED;
.LBB0_1705:
	s_add_u32 s10, s8, 0xffea0080
	s_addc_u32 s11, s9, -1
	s_add_i32 s42, 0, 0x10000
	v_add_u32_e32 v36, s42, v150
	ds_read_b128 v[46:49], v36
	ds_read_b128 v[54:57], v36 offset:1024
	ds_read_b128 v[62:65], v36 offset:2048
	ds_read_b128 v[152:155], v36 offset:3072
	s_cmpk_eq_i32 s41, 0x54
	s_cselect_b32 s13, s7, s11
	s_cselect_b32 s12, s6, s10
	s_cselect_b32 s11, s1, s40
	s_cselect_b32 s10, s0, s39
	v_lshl_add_u64 v[36:37], s[8:9], 0, v[0:1]
	s_add_i32 m0, s24, 0xc000
	ds_read_b128 v[156:159], v151
	ds_read_b128 v[160:163], v151 offset:1024
	ds_read_b128 v[164:167], v151 offset:2048
	ds_read_b128 v[168:171], v151 offset:3072
	ds_read_b128 v[172:175], v151 offset:4096
	ds_read_b128 v[176:179], v151 offset:5120
	ds_read_b128 v[184:187], v151 offset:6144
	ds_read_b128 v[188:191], v151 offset:7168
	global_load_lds_dwordx4 v[36:37], off
	v_lshl_add_u64 v[36:37], s[8:9], 0, v[34:35]
	s_add_i32 m0, s24, 0xe000
	s_nop 0
	global_load_lds_dwordx4 v[36:37], off
	s_waitcnt lgkmcnt(8)
	s_barrier
	s_waitcnt lgkmcnt(0)
	s_setprio 1
	s_waitcnt lgkmcnt(0)
	v_mfma_f32_16x16x32_bf16 v[142:145], v[46:49], v[156:159], v[142:145]
	v_mfma_f32_16x16x32_bf16 v[138:141], v[62:65], v[156:159], v[138:141]
	v_mfma_f32_16x16x32_bf16 v[126:129], v[46:49], v[164:167], v[126:129]
	v_mfma_f32_16x16x32_bf16 v[122:125], v[62:65], v[164:167], v[122:125]
	v_mfma_f32_16x16x32_bf16 v[110:113], v[46:49], v[172:175], v[110:113]
	v_mfma_f32_16x16x32_bf16 v[106:109], v[62:65], v[172:175], v[106:109]
	v_mfma_f32_16x16x32_bf16 v[94:97], v[46:49], v[184:187], v[94:97]
	v_mfma_f32_16x16x32_bf16 v[90:93], v[62:65], v[184:187], v[90:93]
	v_mfma_f32_16x16x32_bf16 v[142:145], v[54:57], v[160:163], v[142:145]
	v_mfma_f32_16x16x32_bf16 v[138:141], v[152:155], v[160:163], v[138:141]
	v_mfma_f32_16x16x32_bf16 v[126:129], v[54:57], v[168:171], v[126:129]
	v_mfma_f32_16x16x32_bf16 v[122:125], v[152:155], v[168:171], v[122:125]
	v_mfma_f32_16x16x32_bf16 v[110:113], v[54:57], v[176:179], v[110:113]
	v_mfma_f32_16x16x32_bf16 v[106:109], v[152:155], v[176:179], v[106:109]
	v_mfma_f32_16x16x32_bf16 v[94:97], v[54:57], v[188:191], v[94:97]
	v_mfma_f32_16x16x32_bf16 v[90:93], v[152:155], v[188:191], v[90:93]
	s_setprio 0
	s_barrier
	s_add_i32 s44, 0, 0x14000
	s_add_i32 s42, s42, s18
	v_add_u32_e32 v36, s44, v150
	v_lshl_add_u64 v[146:147], s[10:11], 0, v[0:1]
	s_mov_b32 m0, s42
	ds_read_b128 v[202:205], v36
	ds_read_b128 v[206:209], v36 offset:1024
	ds_read_b128 v[210:213], v36 offset:2048
	ds_read_b128 v[214:217], v36 offset:3072
	global_load_lds_dwordx4 v[146:147], off
	v_lshl_add_u64 v[180:181], s[10:11], 0, v[34:35]
	s_add_i32 m0, s42, 0x2000
	s_nop 0
	global_load_lds_dwordx4 v[180:181], off
	s_barrier
	s_waitcnt lgkmcnt(0)
	s_setprio 1
	s_waitcnt lgkmcnt(0)
	v_mfma_f32_16x16x32_bf16 v[134:137], v[202:205], v[156:159], v[134:137]
	v_mfma_f32_16x16x32_bf16 v[130:133], v[210:213], v[156:159], v[130:133]
	v_mfma_f32_16x16x32_bf16 v[118:121], v[202:205], v[164:167], v[118:121]
	v_mfma_f32_16x16x32_bf16 v[114:117], v[210:213], v[164:167], v[114:117]
	v_mfma_f32_16x16x32_bf16 v[102:105], v[202:205], v[172:175], v[102:105]
	v_mfma_f32_16x16x32_bf16 v[98:101], v[210:213], v[172:175], v[98:101]
	v_mfma_f32_16x16x32_bf16 v[86:89], v[202:205], v[184:187], v[86:89]
	v_mfma_f32_16x16x32_bf16 v[82:85], v[210:213], v[184:187], v[82:85]
	v_mfma_f32_16x16x32_bf16 v[134:137], v[206:209], v[160:163], v[134:137]
	v_mfma_f32_16x16x32_bf16 v[130:133], v[214:217], v[160:163], v[130:133]
	v_mfma_f32_16x16x32_bf16 v[118:121], v[206:209], v[168:171], v[118:121]
	v_mfma_f32_16x16x32_bf16 v[114:117], v[214:217], v[168:171], v[114:117]
	v_mfma_f32_16x16x32_bf16 v[102:105], v[206:209], v[176:179], v[102:105]
	v_mfma_f32_16x16x32_bf16 v[98:101], v[214:217], v[176:179], v[98:101]
	v_mfma_f32_16x16x32_bf16 v[86:89], v[206:209], v[188:191], v[86:89]
	v_mfma_f32_16x16x32_bf16 v[82:85], v[214:217], v[188:191], v[82:85]
	s_setprio 0
	s_mov_b32 m0, s24
	v_lshl_add_u64 v[182:183], s[12:13], 0, v[0:1]
	s_barrier
	ds_read_b128 v[156:159], v151 offset:16384
	ds_read_b128 v[160:163], v151 offset:17408
	ds_read_b128 v[164:167], v151 offset:18432
	ds_read_b128 v[168:171], v151 offset:19456
	ds_read_b128 v[172:175], v151 offset:20480
	ds_read_b128 v[176:179], v151 offset:21504
	ds_read_b128 v[184:187], v151 offset:22528
	ds_read_b128 v[188:191], v151 offset:23552
	global_load_lds_dwordx4 v[182:183], off
	v_lshl_add_u64 v[194:195], s[12:13], 0, v[34:35]
	s_mov_b32 m0, s25
	s_nop 0
	global_load_lds_dwordx4 v[194:195], off
	s_barrier
	s_waitcnt lgkmcnt(0)
	s_setprio 1
	s_waitcnt lgkmcnt(0)
	v_mfma_f32_16x16x32_bf16 v[78:81], v[46:49], v[156:159], v[78:81]
	v_mfma_f32_16x16x32_bf16 v[74:77], v[62:65], v[156:159], v[74:77]
	v_mfma_f32_16x16x32_bf16 v[58:61], v[46:49], v[164:167], v[58:61]
	v_mfma_f32_16x16x32_bf16 v[50:53], v[62:65], v[164:167], v[50:53]
	v_mfma_f32_16x16x32_bf16 v[30:33], v[46:49], v[172:175], v[30:33]
	v_mfma_f32_16x16x32_bf16 v[26:29], v[62:65], v[172:175], v[26:29]
	v_mfma_f32_16x16x32_bf16 v[14:17], v[46:49], v[184:187], v[14:17]
	v_mfma_f32_16x16x32_bf16 v[10:13], v[62:65], v[184:187], v[10:13]
	v_mfma_f32_16x16x32_bf16 v[78:81], v[54:57], v[160:163], v[78:81]
	v_mfma_f32_16x16x32_bf16 v[74:77], v[152:155], v[160:163], v[74:77]
	v_mfma_f32_16x16x32_bf16 v[58:61], v[54:57], v[168:171], v[58:61]
	v_mfma_f32_16x16x32_bf16 v[50:53], v[152:155], v[168:171], v[50:53]
	v_mfma_f32_16x16x32_bf16 v[30:33], v[54:57], v[176:179], v[30:33]
	v_mfma_f32_16x16x32_bf16 v[26:29], v[152:155], v[176:179], v[26:29]
	v_mfma_f32_16x16x32_bf16 v[14:17], v[54:57], v[188:191], v[14:17]
	v_mfma_f32_16x16x32_bf16 v[10:13], v[152:155], v[188:191], v[10:13]
	s_setprio 0
	s_barrier
; #define PG8_STAGE(bufoff, gbase, voff) do { _Pragma("unroll") for (int _i = 0; _i < 2; ++_i) \
;         __builtin_amdgcn_global_load_lds((const unsigned*)((const char*)(gbase) + (voff)[_i]), (LAS unsigned*)(lds + (bufoff) + ldsw + _i * 8192), 16, 0, 0); } while (0)
; #define PG8_LDA(dst, b, h) do { _Pragma("unroll") for (int m = 0; m < 4; ++m) _Pragma("unroll") for (int k = 0; k < 2; ++k) dst[m][k] = *(const LAS bf16x8*)(lds + PG8_SA(b, h) + aoff + m * 2048 + k * 1024); } while (0)
; #define PG8_LDB(dst, b, h) do { _Pragma("unroll") for (int n = 0; n < 2; ++n) _Pragma("unroll") for (int k = 0; k < 2; ++k) dst[n][k] = *(const LAS bf16x8*)(lds + PG8_SB(b, h) + boff + n * 2048 + k * 1024); } while (0)
; #define PG8_MMA(ai, bj, At, Bt) do { __builtin_amdgcn_s_setprio(1); _Pragma("unroll") for (int m = 0; m < 4; ++m) _Pragma("unroll") for (int n = 0; n < 2; ++n) _Pragma("unroll") for (int k = 0; k < 2; ++k) \
;         acc[ai][bj][m][n] = __builtin_amdgcn_mfma_f32_16x16x32_bf16(Bt[n][k], At[m][k], acc[ai][bj][m][n], 0, 0, 0); __builtin_amdgcn_s_setprio(0); } while (0)
; #define PG8_WAIT_V(n) asm volatile("s_waitcnt vmcnt(" #n ")" ::: "memory")
; #define PG8_WAIT_L(n) asm volatile("s_waitcnt lgkmcnt(" #n ")" ::: "memory")
; #define PG8_BAR __builtin_amdgcn_s_barrier()
; #define PG8_SCHED __builtin_amdgcn_sched_barrier(0)
; template <class Epi, class SchedT>
; DI void gemm_phase(LAS unsigned char* lds, const Gemm g, const SchedT& S, const Epi& E) {
;     ...
;             PG8_STAGE(PG8_SB(0, 1), b2 + hstepB, voffB);
;             PG8_WAIT_V(6); PG8_BAR; PG8_MMA(1, 1, At, B1); PG8_BAR;
;             PG8_LDB(B0, 1, 0); PG8_SCHED; PG8_LDA(At, 1, 0); PG8_STAGE(PG8_SA(0, 1), a2 + hstepA, voffA);
;             PG8_WAIT_L(8); PG8_BAR; PG8_WAIT_L(0); PG8_MMA(0, 0, At, B0); PG8_BAR; PG8_SCHED;
;             PG8_LDB(B1, 1, 1); PG8_STAGE(PG8_SB(1, 0), b3, voffB);
;             PG8_BAR; PG8_WAIT_L(0); PG8_MMA(0, 1, At, B1); PG8_BAR;
;             PG8_LDA(At, 1, 1); PG8_STAGE(PG8_SA(1, 0), a3, voffA);
;             PG8_BAR; PG8_WAIT_L(0); PG8_MMA(1, 0, At, B0); PG8_BAR; PG8_SCHED;
	s_add_u32 s42, s10, 0x160000
	s_addc_u32 s43, s11, 0
	s_add_i32 s44, s44, s18
	v_lshl_add_u64 v[36:37], s[42:43], 0, v[0:1]
	s_mov_b32 m0, s44
	s_nop 0
	global_load_lds_dwordx4 v[36:37], off
	v_lshl_add_u64 v[36:37], s[42:43], 0, v[34:35]
	s_add_i32 m0, s44, 0x2000
	s_nop 0
	global_load_lds_dwordx4 v[36:37], off
	s_waitcnt vmcnt(6)
	s_barrier
	s_setprio 1
	v_mfma_f32_16x16x32_bf16 v[42:45], v[202:205], v[164:167], v[42:45]
	v_mfma_f32_16x16x32_bf16 v[36:39], v[210:213], v[164:167], v[38:41]
	v_mfma_f32_16x16x32_bf16 v[22:25], v[202:205], v[172:175], v[22:25]
	v_mfma_f32_16x16x32_bf16 v[18:21], v[210:213], v[172:175], v[18:21]
	v_mfma_f32_16x16x32_bf16 v[6:9], v[202:205], v[184:187], v[6:9]
	v_mfma_f32_16x16x32_bf16 v[2:5], v[210:213], v[184:187], v[2:5]
	v_mfma_f32_16x16x32_bf16 v[46:49], v[202:205], v[156:159], v[70:73]
	v_mfma_f32_16x16x32_bf16 v[54:57], v[210:213], v[156:159], v[66:69]
	v_mfma_f32_16x16x32_bf16 v[42:45], v[206:209], v[168:171], v[42:45]
	v_mfma_f32_16x16x32_bf16 v[36:39], v[214:217], v[168:171], v[36:39]
	v_mfma_f32_16x16x32_bf16 v[22:25], v[206:209], v[176:179], v[22:25]
	v_mfma_f32_16x16x32_bf16 v[18:21], v[214:217], v[176:179], v[18:21]
	v_mfma_f32_16x16x32_bf16 v[6:9], v[206:209], v[188:191], v[6:9]
	v_mfma_f32_16x16x32_bf16 v[2:5], v[214:217], v[188:191], v[2:5]
	v_mfma_f32_16x16x32_bf16 v[46:49], v[206:209], v[160:163], v[46:49]
	v_mfma_f32_16x16x32_bf16 v[54:57], v[214:217], v[160:163], v[54:57]
	s_setprio 0
	s_add_i32 s42, 0, 0x18000
	v_add_u32_e32 v40, s42, v150
	s_barrier
	ds_read_b128 v[62:65], v40
	ds_read_b128 v[66:69], v40 offset:1024
	ds_read_b128 v[70:73], v40 offset:2048
	ds_read_b128 v[152:155], v40 offset:3072
	s_add_u32 s12, s12, 0x160000
	s_addc_u32 s13, s13, 0
	s_mov_b32 m0, s26
	v_lshl_add_u64 v[40:41], s[12:13], 0, v[0:1]
	ds_read_b128 v[156:159], v151 offset:32768
	ds_read_b128 v[160:163], v151 offset:33792
	ds_read_b128 v[164:167], v151 offset:34816
	ds_read_b128 v[168:171], v151 offset:35840
	ds_read_b128 v[172:175], v151 offset:36864
	ds_read_b128 v[176:179], v151 offset:37888
	ds_read_b128 v[184:187], v151 offset:38912
	ds_read_b128 v[188:191], v151 offset:39936
	global_load_lds_dwordx4 v[40:41], off
	v_lshl_add_u64 v[40:41], s[12:13], 0, v[34:35]
	s_mov_b32 m0, s27
	s_nop 0
	global_load_lds_dwordx4 v[40:41], off
	s_waitcnt lgkmcnt(8)
	s_barrier
	s_waitcnt lgkmcnt(0)
	s_setprio 1
	s_waitcnt lgkmcnt(0)
	v_mfma_f32_16x16x32_bf16 v[142:145], v[62:65], v[156:159], v[142:145]
	v_mfma_f32_16x16x32_bf16 v[138:141], v[70:73], v[156:159], v[138:141]
	v_mfma_f32_16x16x32_bf16 v[126:129], v[62:65], v[164:167], v[126:129]
	v_mfma_f32_16x16x32_bf16 v[122:125], v[70:73], v[164:167], v[122:125]
	v_mfma_f32_16x16x32_bf16 v[110:113], v[62:65], v[172:175], v[110:113]
	v_mfma_f32_16x16x32_bf16 v[106:109], v[70:73], v[172:175], v[106:109]
	v_mfma_f32_16x16x32_bf16 v[94:97], v[62:65], v[184:187], v[94:97]
	v_mfma_f32_16x16x32_bf16 v[90:93], v[70:73], v[184:187], v[90:93]
	v_mfma_f32_16x16x32_bf16 v[142:145], v[66:69], v[160:163], v[142:145]
	v_mfma_f32_16x16x32_bf16 v[138:141], v[152:155], v[160:163], v[138:141]
	v_mfma_f32_16x16x32_bf16 v[126:129], v[66:69], v[168:171], v[126:129]
	v_mfma_f32_16x16x32_bf16 v[122:125], v[152:155], v[168:171], v[122:125]
	v_mfma_f32_16x16x32_bf16 v[110:113], v[66:69], v[176:179], v[110:113]
	v_mfma_f32_16x16x32_bf16 v[106:109], v[152:155], v[176:179], v[106:109]
	v_mfma_f32_16x16x32_bf16 v[94:97], v[66:69], v[188:191], v[94:97]
	v_mfma_f32_16x16x32_bf16 v[90:93], v[152:155], v[188:191], v[90:93]
	s_setprio 0
	s_barrier
	s_add_i32 s12, 0, 0x1c000
	v_add_u32_e32 v40, s12, v150
	s_add_i32 s13, s42, s18
	ds_read_b128 v[202:205], v40
	ds_read_b128 v[206:209], v40 offset:1024
	ds_read_b128 v[210:213], v40 offset:2048
	ds_read_b128 v[214:217], v40 offset:3072
	v_lshl_add_u64 v[40:41], v[146:147], 0, s[90:91]
	s_mov_b32 m0, s13
	s_nop 0
	global_load_lds_dwordx4 v[40:41], off
	v_lshl_add_u64 v[40:41], v[180:181], 0, s[90:91]
	s_add_i32 m0, s13, 0x2000
	s_nop 0
	global_load_lds_dwordx4 v[40:41], off
	s_barrier
	s_waitcnt lgkmcnt(0)
	s_setprio 1
	s_waitcnt lgkmcnt(0)
	v_mfma_f32_16x16x32_bf16 v[134:137], v[202:205], v[156:159], v[134:137]
	v_mfma_f32_16x16x32_bf16 v[130:133], v[210:213], v[156:159], v[130:133]
	v_mfma_f32_16x16x32_bf16 v[118:121], v[202:205], v[164:167], v[118:121]
	v_mfma_f32_16x16x32_bf16 v[114:117], v[210:213], v[164:167], v[114:117]
	v_mfma_f32_16x16x32_bf16 v[102:105], v[202:205], v[172:175], v[102:105]
	v_mfma_f32_16x16x32_bf16 v[98:101], v[210:213], v[172:175], v[98:101]
	v_mfma_f32_16x16x32_bf16 v[86:89], v[202:205], v[184:187], v[86:89]
	v_mfma_f32_16x16x32_bf16 v[82:85], v[210:213], v[184:187], v[82:85]
	v_mfma_f32_16x16x32_bf16 v[134:137], v[206:209], v[160:163], v[134:137]
	v_mfma_f32_16x16x32_bf16 v[130:133], v[214:217], v[160:163], v[130:133]
	v_mfma_f32_16x16x32_bf16 v[118:121], v[206:209], v[168:171], v[118:121]
	v_mfma_f32_16x16x32_bf16 v[114:117], v[214:217], v[168:171], v[114:117]
	v_mfma_f32_16x16x32_bf16 v[102:105], v[206:209], v[176:179], v[102:105]
	v_mfma_f32_16x16x32_bf16 v[98:101], v[214:217], v[176:179], v[98:101]
	v_mfma_f32_16x16x32_bf16 v[86:89], v[206:209], v[188:191], v[86:89]
	v_mfma_f32_16x16x32_bf16 v[82:85], v[214:217], v[188:191], v[82:85]
	s_setprio 0
	s_mov_b32 m0, s31
	v_lshl_add_u64 v[40:41], v[182:183], 0, s[90:91]
	s_barrier
	ds_read_b128 v[156:159], v151 offset:49152
	ds_read_b128 v[160:163], v151 offset:50176
	ds_read_b128 v[164:167], v151 offset:51200
	ds_read_b128 v[168:171], v151 offset:52224
	ds_read_b128 v[172:175], v151 offset:53248
	ds_read_b128 v[176:179], v151 offset:54272
	ds_read_b128 v[184:187], v151 offset:55296
	ds_read_b128 v[188:191], v151 offset:56320
	global_load_lds_dwordx4 v[40:41], off
	v_lshl_add_u64 v[40:41], v[194:195], 0, s[90:91]
	s_mov_b32 m0, s34
	s_nop 0
	global_load_lds_dwordx4 v[40:41], off
	s_barrier
; #define PG8_STAGE(bufoff, gbase, voff) do { _Pragma("unroll") for (int _i = 0; _i < 2; ++_i) \
;         __builtin_amdgcn_global_load_lds((const unsigned*)((const char*)(gbase) + (voff)[_i]), (LAS unsigned*)(lds + (bufoff) + ldsw + _i * 8192), 16, 0, 0); } while (0)
; #define PG8_MMA(ai, bj, At, Bt) do { __builtin_amdgcn_s_setprio(1); _Pragma("unroll") for (int m = 0; m < 4; ++m) _Pragma("unroll") for (int n = 0; n < 2; ++n) _Pragma("unroll") for (int k = 0; k < 2; ++k) \
;         acc[ai][bj][m][n] = __builtin_amdgcn_mfma_f32_16x16x32_bf16(Bt[n][k], At[m][k], acc[ai][bj][m][n], 0, 0, 0); __builtin_amdgcn_s_setprio(0); } while (0)
; #define PG8_WAIT_V(n) asm volatile("s_waitcnt vmcnt(" #n ")" ::: "memory")
; #define PG8_WAIT_L(n) asm volatile("s_waitcnt lgkmcnt(" #n ")" ::: "memory")
; #define PG8_BAR __builtin_amdgcn_s_barrier()
; #define PG8_SCHED __builtin_amdgcn_sched_barrier(0)
; template <class Epi, class SchedT>
; DI void gemm_phase(LAS unsigned char* lds, const Gemm g, const SchedT& S, const Epi& E) {
;     ...
;             PG8_BAR; PG8_WAIT_L(0); PG8_MMA(1, 0, At, B0); PG8_BAR; PG8_SCHED;
;             PG8_STAGE(PG8_SB(1, 1), b3 + hstepB, voffB);
;             PG8_WAIT_V(6); PG8_BAR; PG8_MMA(1, 1, At, B1); PG8_BAR;
;         }
;         { int fr2 = fr, fq2 = fq, wr2 = wr, wc2 = wc; asm volatile("" : "+v"(fr2), "+v"(fq2), "+s"(wr2), "+s"(wc2));
;           E(acc, cur, wr2, wc2, fr2, fq2); }
	s_waitcnt lgkmcnt(0)
	s_setprio 1
	s_waitcnt lgkmcnt(0)
	v_mfma_f32_16x16x32_bf16 v[78:81], v[62:65], v[156:159], v[78:81]
	v_mfma_f32_16x16x32_bf16 v[74:77], v[70:73], v[156:159], v[74:77]
	v_mfma_f32_16x16x32_bf16 v[58:61], v[62:65], v[164:167], v[58:61]
	v_mfma_f32_16x16x32_bf16 v[50:53], v[70:73], v[164:167], v[50:53]
	v_mfma_f32_16x16x32_bf16 v[30:33], v[62:65], v[172:175], v[30:33]
	v_mfma_f32_16x16x32_bf16 v[26:29], v[70:73], v[172:175], v[26:29]
	v_mfma_f32_16x16x32_bf16 v[14:17], v[62:65], v[184:187], v[14:17]
	v_mfma_f32_16x16x32_bf16 v[10:13], v[70:73], v[184:187], v[10:13]
	v_mfma_f32_16x16x32_bf16 v[78:81], v[66:69], v[160:163], v[78:81]
	v_mfma_f32_16x16x32_bf16 v[74:77], v[152:155], v[160:163], v[74:77]
	v_mfma_f32_16x16x32_bf16 v[58:61], v[66:69], v[168:171], v[58:61]
	v_mfma_f32_16x16x32_bf16 v[50:53], v[152:155], v[168:171], v[50:53]
	v_mfma_f32_16x16x32_bf16 v[30:33], v[66:69], v[176:179], v[30:33]
	v_mfma_f32_16x16x32_bf16 v[26:29], v[152:155], v[176:179], v[26:29]
	v_mfma_f32_16x16x32_bf16 v[14:17], v[66:69], v[188:191], v[14:17]
	v_mfma_f32_16x16x32_bf16 v[10:13], v[152:155], v[188:191], v[10:13]
	s_setprio 0
	s_barrier
	s_add_u32 s10, s10, 0x160080
	s_addc_u32 s11, s11, 0
	s_add_i32 s12, s12, s18
	v_lshl_add_u64 v[40:41], s[10:11], 0, v[0:1]
	s_mov_b32 m0, s12
	s_nop 0
	global_load_lds_dwordx4 v[40:41], off
	v_lshl_add_u64 v[40:41], s[10:11], 0, v[34:35]
	s_add_i32 m0, s12, 0x2000
	s_nop 0
	global_load_lds_dwordx4 v[40:41], off
	s_waitcnt vmcnt(6)
	s_barrier
	s_setprio 1
	v_mfma_f32_16x16x32_bf16 v[46:49], v[202:205], v[156:159], v[46:49]
	v_mfma_f32_16x16x32_bf16 v[70:73], v[206:209], v[160:163], v[46:49]
	v_mfma_f32_16x16x32_bf16 v[46:49], v[210:213], v[156:159], v[54:57]
	v_mfma_f32_16x16x32_bf16 v[40:43], v[202:205], v[164:167], v[42:45]
	v_mfma_f32_16x16x32_bf16 v[36:39], v[210:213], v[164:167], v[36:39]
	v_mfma_f32_16x16x32_bf16 v[22:25], v[202:205], v[172:175], v[22:25]
	v_mfma_f32_16x16x32_bf16 v[18:21], v[210:213], v[172:175], v[18:21]
	v_mfma_f32_16x16x32_bf16 v[6:9], v[202:205], v[184:187], v[6:9]
	v_mfma_f32_16x16x32_bf16 v[2:5], v[210:213], v[184:187], v[2:5]
	v_mfma_f32_16x16x32_bf16 v[66:69], v[214:217], v[160:163], v[46:49]
	v_mfma_f32_16x16x32_bf16 v[42:45], v[206:209], v[168:171], v[40:43]
	v_mfma_f32_16x16x32_bf16 v[38:41], v[214:217], v[168:171], v[36:39]
	v_mfma_f32_16x16x32_bf16 v[22:25], v[206:209], v[176:179], v[22:25]
	v_mfma_f32_16x16x32_bf16 v[18:21], v[214:217], v[176:179], v[18:21]
	v_mfma_f32_16x16x32_bf16 v[6:9], v[206:209], v[188:191], v[6:9]
	v_mfma_f32_16x16x32_bf16 v[2:5], v[214:217], v[188:191], v[2:5]
	s_setprio 0
	s_add_i32 s41, s41, 2
	s_add_u32 s8, s8, 0x100
	s_addc_u32 s9, s9, 0
	s_add_u32 s39, s39, 0x100
	s_addc_u32 s40, s40, 0
	s_cmpk_gt_u32 s41, 0x55
	s_barrier
	s_cbranch_scc0 .LBB0_1705
	s_cmp_eq_u32 s32, 0
	s_cbranch_scc1 .Lq_epi_normal
	s_sub_u32 s12, s38, 64
	s_lshl_b32 s13, s33, 2
	s_add_u32 s12, s12, s13
	s_lshl_b32 s101, s12, 2
	s_sub_u32 s98, s32, 1
	s_add_u32 s13, s101, s98
	s_lshl_b32 s13, s13, 18
	s_add_u32 s8, s4, 0xcd01000
	s_addc_u32 s9, s5, 0
	s_add_u32 s8, s8, s13
	s_addc_u32 s9, s9, 0
	s_lshl_b32 s13, s12, 2
	s_sub_u32 s10, s4, 0x800
	s_subb_u32 s11, s5, 0
	s_add_u32 s10, s10, s13
	s_addc_u32 s11, s11, 0
	v_lshlrev_b32_e32 v202, 4, v192
	global_store_dwordx4 v202, v[2:5], s[8:9] sc0 sc1
	s_add_u32 s8, s8, 0x2000
	s_addc_u32 s9, s9, 0
	global_store_dwordx4 v202, v[6:9], s[8:9] sc0 sc1
	s_add_u32 s8, s8, 0x2000
	s_addc_u32 s9, s9, 0
	global_store_dwordx4 v202, v[10:13], s[8:9] sc0 sc1
	s_add_u32 s8, s8, 0x2000
	s_addc_u32 s9, s9, 0
	global_store_dwordx4 v202, v[14:17], s[8:9] sc0 sc1
	s_add_u32 s8, s8, 0x2000
	s_addc_u32 s9, s9, 0
	global_store_dwordx4 v202, v[18:21], s[8:9] sc0 sc1
	s_add_u32 s8, s8, 0x2000
	s_addc_u32 s9, s9, 0
	global_store_dwordx4 v202, v[22:25], s[8:9] sc0 sc1
	s_add_u32 s8, s8, 0x2000
	s_addc_u32 s9, s9, 0
	global_store_dwordx4 v202, v[26:29], s[8:9] sc0 sc1
	s_add_u32 s8, s8, 0x2000
	s_addc_u32 s9, s9, 0
	global_store_dwordx4 v202, v[30:33], s[8:9] sc0 sc1
	s_add_u32 s8, s8, 0x2000
	s_addc_u32 s9, s9, 0
	global_store_dwordx4 v202, v[38:41], s[8:9] sc0 sc1
	s_add_u32 s8, s8, 0x2000
	s_addc_u32 s9, s9, 0
	global_store_dwordx4 v202, v[42:45], s[8:9] sc0 sc1
	s_add_u32 s8, s8, 0x2000
	s_addc_u32 s9, s9, 0
	global_store_dwordx4 v202, v[50:53], s[8:9] sc0 sc1
	s_add_u32 s8, s8, 0x2000
	s_addc_u32 s9, s9, 0
	global_store_dwordx4 v202, v[58:61], s[8:9] sc0 sc1
	s_add_u32 s8, s8, 0x2000
	s_addc_u32 s9, s9, 0
	global_store_dwordx4 v202, v[66:69], s[8:9] sc0 sc1
	s_add_u32 s8, s8, 0x2000
	s_addc_u32 s9, s9, 0
	global_store_dwordx4 v202, v[70:73], s[8:9] sc0 sc1
	s_add_u32 s8, s8, 0x2000
	s_addc_u32 s9, s9, 0
	global_store_dwordx4 v202, v[74:77], s[8:9] sc0 sc1
	s_add_u32 s8, s8, 0x2000
	s_addc_u32 s9, s9, 0
	global_store_dwordx4 v202, v[78:81], s[8:9] sc0 sc1
	s_add_u32 s8, s8, 0x2000
	s_addc_u32 s9, s9, 0
	global_store_dwordx4 v202, v[82:85], s[8:9] sc0 sc1
	s_add_u32 s8, s8, 0x2000
	s_addc_u32 s9, s9, 0
	global_store_dwordx4 v202, v[86:89], s[8:9] sc0 sc1
	s_add_u32 s8, s8, 0x2000
	s_addc_u32 s9, s9, 0
	global_store_dwordx4 v202, v[90:93], s[8:9] sc0 sc1
	s_add_u32 s8, s8, 0x2000
	s_addc_u32 s9, s9, 0
	global_store_dwordx4 v202, v[94:97], s[8:9] sc0 sc1
	s_add_u32 s8, s8, 0x2000
	s_addc_u32 s9, s9, 0
	global_store_dwordx4 v202, v[98:101], s[8:9] sc0 sc1
	s_add_u32 s8, s8, 0x2000
	s_addc_u32 s9, s9, 0
	global_store_dwordx4 v202, v[102:105], s[8:9] sc0 sc1
	s_add_u32 s8, s8, 0x2000
	s_addc_u32 s9, s9, 0
	global_store_dwordx4 v202, v[106:109], s[8:9] sc0 sc1
	s_add_u32 s8, s8, 0x2000
	s_addc_u32 s9, s9, 0
	global_store_dwordx4 v202, v[110:113], s[8:9] sc0 sc1
	s_add_u32 s8, s8, 0x2000
	s_addc_u32 s9, s9, 0
	global_store_dwordx4 v202, v[114:117], s[8:9] sc0 sc1
	s_add_u32 s8, s8, 0x2000
	s_addc_u32 s9, s9, 0
	global_store_dwordx4 v202, v[118:121], s[8:9] sc0 sc1
	s_add_u32 s8, s8, 0x2000
	s_addc_u32 s9, s9, 0
	global_store_dwordx4 v202, v[122:125], s[8:9] sc0 sc1
	s_add_u32 s8, s8, 0x2000
	s_addc_u32 s9, s9, 0
	global_store_dwordx4 v202, v[126:129], s[8:9] sc0 sc1
	s_add_u32 s8, s8, 0x2000
	s_addc_u32 s9, s9, 0
	global_store_dwordx4 v202, v[130:133], s[8:9] sc0 sc1
	s_add_u32 s8, s8, 0x2000
	s_addc_u32 s9, s9, 0
	global_store_dwordx4 v202, v[134:137], s[8:9] sc0 sc1
	s_add_u32 s8, s8, 0x2000
	s_addc_u32 s9, s9, 0
	global_store_dwordx4 v202, v[138:141], s[8:9] sc0 sc1
	s_add_u32 s8, s8, 0x2000
	s_addc_u32 s9, s9, 0
	global_store_dwordx4 v202, v[142:145], s[8:9] sc0 sc1
	s_add_u32 s8, s8, 0x2000
	s_addc_u32 s9, s9, 0
	s_waitcnt vmcnt(0)
	s_barrier
	v_cmp_eq_u32_e32 vcc, 0, v192
	s_and_saveexec_b64 s[98:99], vcc
	s_cbranch_execz .Lq_t0done
	buffer_wbl2 sc1
	s_waitcnt vmcnt(0)
	v_mov_b32_e32 v203, 1
	v_mov_b32_e32 v204, 0
	global_atomic_add v203, v204, v203, s[10:11] sc0
	s_waitcnt vmcnt(0)
	buffer_inv sc1
	s_waitcnt vmcnt(0)
	v_mov_b32_e32 v204, 0x20400
	ds_write_b32 v204, v203
	s_waitcnt lgkmcnt(0)

; template <class Epi, class SchedT>
; DI void gemm_phase(LAS unsigned char* lds, const Gemm g, const SchedT& S, const Epi& E) {
;     ...
;         { int fr2 = fr, fq2 = fq, wr2 = wr, wc2 = wc; asm volatile("" : "+v"(fr2), "+v"(fq2), "+s"(wr2), "+s"(wc2));
;           E(acc, cur, wr2, wc2, fr2, fq2); }
.Lq_last:
	s_lshl_b32 s13, s101, 18
	s_add_u32 s8, s4, 0xcd01000
	s_addc_u32 s9, s5, 0
	s_add_u32 s8, s8, s13
	s_addc_u32 s9, s9, 0
	global_load_dwordx4 v[2:5], v202, s[8:9]
	s_add_u32 s8, s8, 0x2000
	s_addc_u32 s9, s9, 0
	global_load_dwordx4 v[6:9], v202, s[8:9]
	s_add_u32 s8, s8, 0x2000
	s_addc_u32 s9, s9, 0
	global_load_dwordx4 v[10:13], v202, s[8:9]
	s_add_u32 s8, s8, 0x2000
	s_addc_u32 s9, s9, 0
	global_load_dwordx4 v[14:17], v202, s[8:9]
	s_add_u32 s8, s8, 0x2000
	s_addc_u32 s9, s9, 0
	global_load_dwordx4 v[18:21], v202, s[8:9]
	s_add_u32 s8, s8, 0x2000
	s_addc_u32 s9, s9, 0
	global_load_dwordx4 v[22:25], v202, s[8:9]
	s_add_u32 s8, s8, 0x2000
	s_addc_u32 s9, s9, 0
	global_load_dwordx4 v[26:29], v202, s[8:9]
	s_add_u32 s8, s8, 0x2000
	s_addc_u32 s9, s9, 0
	global_load_dwordx4 v[30:33], v202, s[8:9]
	s_add_u32 s8, s8, 0x2000
	s_addc_u32 s9, s9, 0
	global_load_dwordx4 v[38:41], v202, s[8:9]
	s_add_u32 s8, s8, 0x2000
	s_addc_u32 s9, s9, 0
	global_load_dwordx4 v[42:45], v202, s[8:9]
	s_add_u32 s8, s8, 0x2000
	s_addc_u32 s9, s9, 0
	global_load_dwordx4 v[50:53], v202, s[8:9]
	s_add_u32 s8, s8, 0x2000
	s_addc_u32 s9, s9, 0
	global_load_dwordx4 v[58:61], v202, s[8:9]
	s_add_u32 s8, s8, 0x2000
	s_addc_u32 s9, s9, 0
	global_load_dwordx4 v[66:69], v202, s[8:9]
	s_add_u32 s8, s8, 0x2000
	s_addc_u32 s9, s9, 0
	global_load_dwordx4 v[70:73], v202, s[8:9]
	s_add_u32 s8, s8, 0x2000
	s_addc_u32 s9, s9, 0
	global_load_dwordx4 v[74:77], v202, s[8:9]
	s_add_u32 s8, s8, 0x2000
	s_addc_u32 s9, s9, 0
	global_load_dwordx4 v[78:81], v202, s[8:9]
	s_add_u32 s8, s8, 0x2000
	s_addc_u32 s9, s9, 0
	global_load_dwordx4 v[82:85], v202, s[8:9]
	s_add_u32 s8, s8, 0x2000
	s_addc_u32 s9, s9, 0
	global_load_dwordx4 v[86:89], v202, s[8:9]
	s_add_u32 s8, s8, 0x2000
	s_addc_u32 s9, s9, 0
	global_load_dwordx4 v[90:93], v202, s[8:9]
	s_add_u32 s8, s8, 0x2000
	s_addc_u32 s9, s9, 0
	global_load_dwordx4 v[94:97], v202, s[8:9]
	s_add_u32 s8, s8, 0x2000
	s_addc_u32 s9, s9, 0
	global_load_dwordx4 v[98:101], v202, s[8:9]
	s_add_u32 s8, s8, 0x2000
	s_addc_u32 s9, s9, 0
	global_load_dwordx4 v[102:105], v202, s[8:9]
	s_add_u32 s8, s8, 0x2000
	s_addc_u32 s9, s9, 0
	global_load_dwordx4 v[106:109], v202, s[8:9]
	s_add_u32 s8, s8, 0x2000
	s_addc_u32 s9, s9, 0
	global_load_dwordx4 v[110:113], v202, s[8:9]
	s_add_u32 s8, s8, 0x2000
	s_addc_u32 s9, s9, 0
	global_load_dwordx4 v[114:117], v202, s[8:9]
	s_add_u32 s8, s8, 0x2000
	s_addc_u32 s9, s9, 0
	global_load_dwordx4 v[118:121], v202, s[8:9]
	s_add_u32 s8, s8, 0x2000
	s_addc_u32 s9, s9, 0
	global_load_dwordx4 v[122:125], v202, s[8:9]
	s_add_u32 s8, s8, 0x2000
	s_addc_u32 s9, s9, 0
	global_load_dwordx4 v[126:129], v202, s[8:9]
	s_add_u32 s8, s8, 0x2000
	s_addc_u32 s9, s9, 0
	global_load_dwordx4 v[130:133], v202, s[8:9]
	s_add_u32 s8, s8, 0x2000
	s_addc_u32 s9, s9, 0
	global_load_dwordx4 v[134:137], v202, s[8:9]
	s_add_u32 s8, s8, 0x2000
	s_addc_u32 s9, s9, 0
	global_load_dwordx4 v[138:141], v202, s[8:9]
	s_add_u32 s8, s8, 0x2000
	s_addc_u32 s9, s9, 0
	global_load_dwordx4 v[142:145], v202, s[8:9]
	s_add_u32 s8, s8, 0x2000
	s_addc_u32 s9, s9, 0
	s_waitcnt vmcnt(0)
	global_load_dwordx4 v[156:159], v202, s[8:9]
	s_add_u32 s8, s8, 0x2000
	s_addc_u32 s9, s9, 0
	global_load_dwordx4 v[160:163], v202, s[8:9]
	s_add_u32 s8, s8, 0x2000
	s_addc_u32 s9, s9, 0
	global_load_dwordx4 v[164:167], v202, s[8:9]
	s_add_u32 s8, s8, 0x2000
	s_addc_u32 s9, s9, 0
	global_load_dwordx4 v[168:171], v202, s[8:9]
	s_add_u32 s8, s8, 0x2000
	s_addc_u32 s9, s9, 0
	global_load_dwordx4 v[172:175], v202, s[8:9]
	s_add_u32 s8, s8, 0x2000
	s_addc_u32 s9, s9, 0
	global_load_dwordx4 v[176:179], v202, s[8:9]
	s_add_u32 s8, s8, 0x2000
	s_addc_u32 s9, s9, 0
	global_load_dwordx4 v[184:187], v202, s[8:9]
	s_add_u32 s8, s8, 0x2000
	s_addc_u32 s9, s9, 0
	global_load_dwordx4 v[188:191], v202, s[8:9]
	s_add_u32 s8, s8, 0x2000
	s_addc_u32 s9, s9, 0
	s_waitcnt vmcnt(0)
	v_pk_add_f32 v[2:3], v[2:3], v[156:157]
	v_pk_add_f32 v[4:5], v[4:5], v[158:159]
	v_pk_add_f32 v[6:7], v[6:7], v[160:161]
	v_pk_add_f32 v[8:9], v[8:9], v[162:163]
	v_pk_add_f32 v[10:11], v[10:11], v[164:165]
	v_pk_add_f32 v[12:13], v[12:13], v[166:167]
	v_pk_add_f32 v[14:15], v[14:15], v[168:169]
	v_pk_add_f32 v[16:17], v[16:17], v[170:171]
	v_pk_add_f32 v[18:19], v[18:19], v[172:173]
	v_pk_add_f32 v[20:21], v[20:21], v[174:175]
	v_pk_add_f32 v[22:23], v[22:23], v[176:177]
	v_pk_add_f32 v[24:25], v[24:25], v[178:179]
	v_pk_add_f32 v[26:27], v[26:27], v[184:185]
	v_pk_add_f32 v[28:29], v[28:29], v[186:187]
	v_pk_add_f32 v[30:31], v[30:31], v[188:189]
	v_pk_add_f32 v[32:33], v[32:33], v[190:191]
	global_load_dwordx4 v[156:159], v202, s[8:9]
	s_add_u32 s8, s8, 0x2000
	s_addc_u32 s9, s9, 0
	global_load_dwordx4 v[160:163], v202, s[8:9]
	s_add_u32 s8, s8, 0x2000
	s_addc_u32 s9, s9, 0
	global_load_dwordx4 v[164:167], v202, s[8:9]
	s_add_u32 s8, s8, 0x2000
	s_addc_u32 s9, s9, 0
	global_load_dwordx4 v[168:171], v202, s[8:9]
	s_add_u32 s8, s8, 0x2000
	s_addc_u32 s9, s9, 0
	global_load_dwordx4 v[172:175], v202, s[8:9]
	s_add_u32 s8, s8, 0x2000
	s_addc_u32 s9, s9, 0
	global_load_dwordx4 v[176:179], v202, s[8:9]
	s_add_u32 s8, s8, 0x2000
	s_addc_u32 s9, s9, 0
	global_load_dwordx4 v[184:187], v202, s[8:9]
	s_add_u32 s8, s8, 0x2000
	s_addc_u32 s9, s9, 0
	global_load_dwordx4 v[188:191], v202, s[8:9]
	s_add_u32 s8, s8, 0x2000
	s_addc_u32 s9, s9, 0
	s_waitcnt vmcnt(0)
; template <class Epi, class SchedT>
; DI void gemm_phase(LAS unsigned char* lds, const Gemm g, const SchedT& S, const Epi& E) {
;     ...
;         { int fr2 = fr, fq2 = fq, wr2 = wr, wc2 = wc; asm volatile("" : "+v"(fr2), "+v"(fq2), "+s"(wr2), "+s"(wc2));
;           E(acc, cur, wr2, wc2, fr2, fq2); }
	v_pk_add_f32 v[38:39], v[38:39], v[156:157]
	v_pk_add_f32 v[40:41], v[40:41], v[158:159]
	v_pk_add_f32 v[42:43], v[42:43], v[160:161]
	v_pk_add_f32 v[44:45], v[44:45], v[162:163]
	v_pk_add_f32 v[50:51], v[50:51], v[164:165]
	v_pk_add_f32 v[52:53], v[52:53], v[166:167]
	v_pk_add_f32 v[58:59], v[58:59], v[168:169]
	v_pk_add_f32 v[60:61], v[60:61], v[170:171]
	v_pk_add_f32 v[66:67], v[66:67], v[172:173]
	v_pk_add_f32 v[68:69], v[68:69], v[174:175]
	v_pk_add_f32 v[70:71], v[70:71], v[176:177]
	v_pk_add_f32 v[72:73], v[72:73], v[178:179]
	v_pk_add_f32 v[74:75], v[74:75], v[184:185]
	v_pk_add_f32 v[76:77], v[76:77], v[186:187]
	v_pk_add_f32 v[78:79], v[78:79], v[188:189]
	v_pk_add_f32 v[80:81], v[80:81], v[190:191]
	global_load_dwordx4 v[156:159], v202, s[8:9]
	s_add_u32 s8, s8, 0x2000
	s_addc_u32 s9, s9, 0
	global_load_dwordx4 v[160:163], v202, s[8:9]
	s_add_u32 s8, s8, 0x2000
	s_addc_u32 s9, s9, 0
	global_load_dwordx4 v[164:167], v202, s[8:9]
	s_add_u32 s8, s8, 0x2000
	s_addc_u32 s9, s9, 0
	global_load_dwordx4 v[168:171], v202, s[8:9]
	s_add_u32 s8, s8, 0x2000
	s_addc_u32 s9, s9, 0
	global_load_dwordx4 v[172:175], v202, s[8:9]
	s_add_u32 s8, s8, 0x2000
	s_addc_u32 s9, s9, 0
	global_load_dwordx4 v[176:179], v202, s[8:9]
	s_add_u32 s8, s8, 0x2000
	s_addc_u32 s9, s9, 0
	global_load_dwordx4 v[184:187], v202, s[8:9]
	s_add_u32 s8, s8, 0x2000
	s_addc_u32 s9, s9, 0
	global_load_dwordx4 v[188:191], v202, s[8:9]
	s_add_u32 s8, s8, 0x2000
	s_addc_u32 s9, s9, 0
	s_waitcnt vmcnt(0)
	v_pk_add_f32 v[82:83], v[82:83], v[156:157]
	v_pk_add_f32 v[84:85], v[84:85], v[158:159]
	v_pk_add_f32 v[86:87], v[86:87], v[160:161]
	v_pk_add_f32 v[88:89], v[88:89], v[162:163]
	v_pk_add_f32 v[90:91], v[90:91], v[164:165]
	v_pk_add_f32 v[92:93], v[92:93], v[166:167]
	v_pk_add_f32 v[94:95], v[94:95], v[168:169]
	v_pk_add_f32 v[96:97], v[96:97], v[170:171]
	v_pk_add_f32 v[98:99], v[98:99], v[172:173]
	v_pk_add_f32 v[100:101], v[100:101], v[174:175]
	v_pk_add_f32 v[102:103], v[102:103], v[176:177]
	v_pk_add_f32 v[104:105], v[104:105], v[178:179]
	v_pk_add_f32 v[106:107], v[106:107], v[184:185]
	v_pk_add_f32 v[108:109], v[108:109], v[186:187]
	v_pk_add_f32 v[110:111], v[110:111], v[188:189]
	v_pk_add_f32 v[112:113], v[112:113], v[190:191]
	global_load_dwordx4 v[156:159], v202, s[8:9]
	s_add_u32 s8, s8, 0x2000
	s_addc_u32 s9, s9, 0
	global_load_dwordx4 v[160:163], v202, s[8:9]
	s_add_u32 s8, s8, 0x2000
	s_addc_u32 s9, s9, 0
	global_load_dwordx4 v[164:167], v202, s[8:9]
	s_add_u32 s8, s8, 0x2000
	s_addc_u32 s9, s9, 0
	global_load_dwordx4 v[168:171], v202, s[8:9]
	s_add_u32 s8, s8, 0x2000
	s_addc_u32 s9, s9, 0
	global_load_dwordx4 v[172:175], v202, s[8:9]
	s_add_u32 s8, s8, 0x2000
	s_addc_u32 s9, s9, 0
	global_load_dwordx4 v[176:179], v202, s[8:9]
	s_add_u32 s8, s8, 0x2000
	s_addc_u32 s9, s9, 0
	global_load_dwordx4 v[184:187], v202, s[8:9]
	s_add_u32 s8, s8, 0x2000
	s_addc_u32 s9, s9, 0
	global_load_dwordx4 v[188:191], v202, s[8:9]
	s_add_u32 s8, s8, 0x2000
	s_addc_u32 s9, s9, 0
	s_waitcnt vmcnt(0)
	v_pk_add_f32 v[114:115], v[114:115], v[156:157]
	v_pk_add_f32 v[116:117], v[116:117], v[158:159]
	v_pk_add_f32 v[118:119], v[118:119], v[160:161]
	v_pk_add_f32 v[120:121], v[120:121], v[162:163]
	v_pk_add_f32 v[122:123], v[122:123], v[164:165]
	v_pk_add_f32 v[124:125], v[124:125], v[166:167]
	v_pk_add_f32 v[126:127], v[126:127], v[168:169]
	v_pk_add_f32 v[128:129], v[128:129], v[170:171]
	v_pk_add_f32 v[130:131], v[130:131], v[172:173]
	v_pk_add_f32 v[132:133], v[132:133], v[174:175]
	v_pk_add_f32 v[134:135], v[134:135], v[176:177]
	v_pk_add_f32 v[136:137], v[136:137], v[178:179]
	v_pk_add_f32 v[138:139], v[138:139], v[184:185]
	v_pk_add_f32 v[140:141], v[140:141], v[186:187]
	v_pk_add_f32 v[142:143], v[142:143], v[188:189]
	v_pk_add_f32 v[144:145], v[144:145], v[190:191]
	global_load_dwordx4 v[156:159], v202, s[8:9]
	s_add_u32 s8, s8, 0x2000
	s_addc_u32 s9, s9, 0
	global_load_dwordx4 v[160:163], v202, s[8:9]
	s_add_u32 s8, s8, 0x2000
	s_addc_u32 s9, s9, 0
	global_load_dwordx4 v[164:167], v202, s[8:9]
	s_add_u32 s8, s8, 0x2000
	s_addc_u32 s9, s9, 0
	global_load_dwordx4 v[168:171], v202, s[8:9]
	s_add_u32 s8, s8, 0x2000
	s_addc_u32 s9, s9, 0
	global_load_dwordx4 v[172:175], v202, s[8:9]
	s_add_u32 s8, s8, 0x2000
	s_addc_u32 s9, s9, 0
	global_load_dwordx4 v[176:179], v202, s[8:9]
	s_add_u32 s8, s8, 0x2000
	s_addc_u32 s9, s9, 0
	global_load_dwordx4 v[184:187], v202, s[8:9]
	s_add_u32 s8, s8, 0x2000
	s_addc_u32 s9, s9, 0
	global_load_dwordx4 v[188:191], v202, s[8:9]
	s_add_u32 s8, s8, 0x2000
	s_addc_u32 s9, s9, 0
	s_waitcnt vmcnt(0)
	v_pk_add_f32 v[2:3], v[2:3], v[156:157]
	v_pk_add_f32 v[4:5], v[4:5], v[158:159]
	v_pk_add_f32 v[6:7], v[6:7], v[160:161]
	v_pk_add_f32 v[8:9], v[8:9], v[162:163]
	v_pk_add_f32 v[10:11], v[10:11], v[164:165]
	v_pk_add_f32 v[12:13], v[12:13], v[166:167]
	v_pk_add_f32 v[14:15], v[14:15], v[168:169]
	v_pk_add_f32 v[16:17], v[16:17], v[170:171]
	v_pk_add_f32 v[18:19], v[18:19], v[172:173]
	v_pk_add_f32 v[20:21], v[20:21], v[174:175]
	v_pk_add_f32 v[22:23], v[22:23], v[176:177]
	v_pk_add_f32 v[24:25], v[24:25], v[178:179]
	v_pk_add_f32 v[26:27], v[26:27], v[184:185]
	v_pk_add_f32 v[28:29], v[28:29], v[186:187]
	v_pk_add_f32 v[30:31], v[30:31], v[188:189]
	v_pk_add_f32 v[32:33], v[32:33], v[190:191]
	global_load_dwordx4 v[156:159], v202, s[8:9]
	s_add_u32 s8, s8, 0x2000
	s_addc_u32 s9, s9, 0
	global_load_dwordx4 v[160:163], v202, s[8:9]
	s_add_u32 s8, s8, 0x2000
	s_addc_u32 s9, s9, 0
	global_load_dwordx4 v[164:167], v202, s[8:9]
	s_add_u32 s8, s8, 0x2000
	s_addc_u32 s9, s9, 0
	global_load_dwordx4 v[168:171], v202, s[8:9]
	s_add_u32 s8, s8, 0x2000
	s_addc_u32 s9, s9, 0
	global_load_dwordx4 v[172:175], v202, s[8:9]
	s_add_u32 s8, s8, 0x2000
	s_addc_u32 s9, s9, 0
	global_load_dwordx4 v[176:179], v202, s[8:9]
	s_add_u32 s8, s8, 0x2000
	s_addc_u32 s9, s9, 0
	global_load_dwordx4 v[184:187], v202, s[8:9]
	s_add_u32 s8, s8, 0x2000
	s_addc_u32 s9, s9, 0
	global_load_dwordx4 v[188:191], v202, s[8:9]
	s_add_u32 s8, s8, 0x2000
	s_addc_u32 s9, s9, 0
	s_waitcnt vmcnt(0)
; template <class Epi, class SchedT>
; DI void gemm_phase(LAS unsigned char* lds, const Gemm g, const SchedT& S, const Epi& E) {
;     ...
;         { int fr2 = fr, fq2 = fq, wr2 = wr, wc2 = wc; asm volatile("" : "+v"(fr2), "+v"(fq2), "+s"(wr2), "+s"(wc2));
;           E(acc, cur, wr2, wc2, fr2, fq2); }
	v_pk_add_f32 v[38:39], v[38:39], v[156:157]
	v_pk_add_f32 v[40:41], v[40:41], v[158:159]
	v_pk_add_f32 v[42:43], v[42:43], v[160:161]
	v_pk_add_f32 v[44:45], v[44:45], v[162:163]
	v_pk_add_f32 v[50:51], v[50:51], v[164:165]
	v_pk_add_f32 v[52:53], v[52:53], v[166:167]
	v_pk_add_f32 v[58:59], v[58:59], v[168:169]
	v_pk_add_f32 v[60:61], v[60:61], v[170:171]
	v_pk_add_f32 v[66:67], v[66:67], v[172:173]
	v_pk_add_f32 v[68:69], v[68:69], v[174:175]
	v_pk_add_f32 v[70:71], v[70:71], v[176:177]
	v_pk_add_f32 v[72:73], v[72:73], v[178:179]
	v_pk_add_f32 v[74:75], v[74:75], v[184:185]
	v_pk_add_f32 v[76:77], v[76:77], v[186:187]
	v_pk_add_f32 v[78:79], v[78:79], v[188:189]
	v_pk_add_f32 v[80:81], v[80:81], v[190:191]
	global_load_dwordx4 v[156:159], v202, s[8:9]
	s_add_u32 s8, s8, 0x2000
	s_addc_u32 s9, s9, 0
	global_load_dwordx4 v[160:163], v202, s[8:9]
	s_add_u32 s8, s8, 0x2000
	s_addc_u32 s9, s9, 0
	global_load_dwordx4 v[164:167], v202, s[8:9]
	s_add_u32 s8, s8, 0x2000
	s_addc_u32 s9, s9, 0
	global_load_dwordx4 v[168:171], v202, s[8:9]
	s_add_u32 s8, s8, 0x2000
	s_addc_u32 s9, s9, 0
	global_load_dwordx4 v[172:175], v202, s[8:9]
	s_add_u32 s8, s8, 0x2000
	s_addc_u32 s9, s9, 0
	global_load_dwordx4 v[176:179], v202, s[8:9]
	s_add_u32 s8, s8, 0x2000
	s_addc_u32 s9, s9, 0
	global_load_dwordx4 v[184:187], v202, s[8:9]
	s_add_u32 s8, s8, 0x2000
	s_addc_u32 s9, s9, 0
	global_load_dwordx4 v[188:191], v202, s[8:9]
	s_add_u32 s8, s8, 0x2000
	s_addc_u32 s9, s9, 0
	s_waitcnt vmcnt(0)
	v_pk_add_f32 v[82:83], v[82:83], v[156:157]
	v_pk_add_f32 v[84:85], v[84:85], v[158:159]
	v_pk_add_f32 v[86:87], v[86:87], v[160:161]
	v_pk_add_f32 v[88:89], v[88:89], v[162:163]
	v_pk_add_f32 v[90:91], v[90:91], v[164:165]
	v_pk_add_f32 v[92:93], v[92:93], v[166:167]
	v_pk_add_f32 v[94:95], v[94:95], v[168:169]
	v_pk_add_f32 v[96:97], v[96:97], v[170:171]
	v_pk_add_f32 v[98:99], v[98:99], v[172:173]
	v_pk_add_f32 v[100:101], v[100:101], v[174:175]
	v_pk_add_f32 v[102:103], v[102:103], v[176:177]
	v_pk_add_f32 v[104:105], v[104:105], v[178:179]
	v_pk_add_f32 v[106:107], v[106:107], v[184:185]
	v_pk_add_f32 v[108:109], v[108:109], v[186:187]
	v_pk_add_f32 v[110:111], v[110:111], v[188:189]
	v_pk_add_f32 v[112:113], v[112:113], v[190:191]
	global_load_dwordx4 v[156:159], v202, s[8:9]
	s_add_u32 s8, s8, 0x2000
	s_addc_u32 s9, s9, 0
	global_load_dwordx4 v[160:163], v202, s[8:9]
	s_add_u32 s8, s8, 0x2000
	s_addc_u32 s9, s9, 0
	global_load_dwordx4 v[164:167], v202, s[8:9]
	s_add_u32 s8, s8, 0x2000
	s_addc_u32 s9, s9, 0
	global_load_dwordx4 v[168:171], v202, s[8:9]
	s_add_u32 s8, s8, 0x2000
	s_addc_u32 s9, s9, 0
	global_load_dwordx4 v[172:175], v202, s[8:9]
	s_add_u32 s8, s8, 0x2000
	s_addc_u32 s9, s9, 0
	global_load_dwordx4 v[176:179], v202, s[8:9]
	s_add_u32 s8, s8, 0x2000
	s_addc_u32 s9, s9, 0
	global_load_dwordx4 v[184:187], v202, s[8:9]
	s_add_u32 s8, s8, 0x2000
	s_addc_u32 s9, s9, 0
	global_load_dwordx4 v[188:191], v202, s[8:9]
	s_add_u32 s8, s8, 0x2000
	s_addc_u32 s9, s9, 0
	s_waitcnt vmcnt(0)
	v_pk_add_f32 v[114:115], v[114:115], v[156:157]
	v_pk_add_f32 v[116:117], v[116:117], v[158:159]
	v_pk_add_f32 v[118:119], v[118:119], v[160:161]
	v_pk_add_f32 v[120:121], v[120:121], v[162:163]
	v_pk_add_f32 v[122:123], v[122:123], v[164:165]
	v_pk_add_f32 v[124:125], v[124:125], v[166:167]
	v_pk_add_f32 v[126:127], v[126:127], v[168:169]
	v_pk_add_f32 v[128:129], v[128:129], v[170:171]
	v_pk_add_f32 v[130:131], v[130:131], v[172:173]
	v_pk_add_f32 v[132:133], v[132:133], v[174:175]
	v_pk_add_f32 v[134:135], v[134:135], v[176:177]
	v_pk_add_f32 v[136:137], v[136:137], v[178:179]
	v_pk_add_f32 v[138:139], v[138:139], v[184:185]
	v_pk_add_f32 v[140:141], v[140:141], v[186:187]
	v_pk_add_f32 v[142:143], v[142:143], v[188:189]
	v_pk_add_f32 v[144:145], v[144:145], v[190:191]
	global_load_dwordx4 v[156:159], v202, s[8:9]
	s_add_u32 s8, s8, 0x2000
	s_addc_u32 s9, s9, 0
	global_load_dwordx4 v[160:163], v202, s[8:9]
	s_add_u32 s8, s8, 0x2000
	s_addc_u32 s9, s9, 0
	global_load_dwordx4 v[164:167], v202, s[8:9]
	s_add_u32 s8, s8, 0x2000
	s_addc_u32 s9, s9, 0
	global_load_dwordx4 v[168:171], v202, s[8:9]
	s_add_u32 s8, s8, 0x2000
	s_addc_u32 s9, s9, 0
	global_load_dwordx4 v[172:175], v202, s[8:9]
	s_add_u32 s8, s8, 0x2000
	s_addc_u32 s9, s9, 0
	global_load_dwordx4 v[176:179], v202, s[8:9]
	s_add_u32 s8, s8, 0x2000
	s_addc_u32 s9, s9, 0
	global_load_dwordx4 v[184:187], v202, s[8:9]
	s_add_u32 s8, s8, 0x2000
	s_addc_u32 s9, s9, 0
	global_load_dwordx4 v[188:191], v202, s[8:9]
	s_add_u32 s8, s8, 0x2000
	s_addc_u32 s9, s9, 0
	s_waitcnt vmcnt(0)
; template <class Epi, class SchedT>
; DI void gemm_phase(LAS unsigned char* lds, const Gemm g, const SchedT& S, const Epi& E) {
;     ...
;         { int fr2 = fr, fq2 = fq, wr2 = wr, wc2 = wc; asm volatile("" : "+v"(fr2), "+v"(fq2), "+s"(wr2), "+s"(wc2));
;           E(acc, cur, wr2, wc2, fr2, fq2); }
	v_pk_add_f32 v[2:3], v[2:3], v[156:157]
	v_pk_add_f32 v[4:5], v[4:5], v[158:159]
	v_pk_add_f32 v[6:7], v[6:7], v[160:161]
	v_pk_add_f32 v[8:9], v[8:9], v[162:163]
	v_pk_add_f32 v[10:11], v[10:11], v[164:165]
	v_pk_add_f32 v[12:13], v[12:13], v[166:167]
	v_pk_add_f32 v[14:15], v[14:15], v[168:169]
	v_pk_add_f32 v[16:17], v[16:17], v[170:171]
	v_pk_add_f32 v[18:19], v[18:19], v[172:173]
	v_pk_add_f32 v[20:21], v[20:21], v[174:175]
	v_pk_add_f32 v[22:23], v[22:23], v[176:177]
	v_pk_add_f32 v[24:25], v[24:25], v[178:179]
	v_pk_add_f32 v[26:27], v[26:27], v[184:185]
	v_pk_add_f32 v[28:29], v[28:29], v[186:187]
	v_pk_add_f32 v[30:31], v[30:31], v[188:189]
	v_pk_add_f32 v[32:33], v[32:33], v[190:191]
	global_load_dwordx4 v[156:159], v202, s[8:9]
	s_add_u32 s8, s8, 0x2000
	s_addc_u32 s9, s9, 0
	global_load_dwordx4 v[160:163], v202, s[8:9]
	s_add_u32 s8, s8, 0x2000
	s_addc_u32 s9, s9, 0
	global_load_dwordx4 v[164:167], v202, s[8:9]
	s_add_u32 s8, s8, 0x2000
	s_addc_u32 s9, s9, 0
	global_load_dwordx4 v[168:171], v202, s[8:9]
	s_add_u32 s8, s8, 0x2000
	s_addc_u32 s9, s9, 0
	global_load_dwordx4 v[172:175], v202, s[8:9]
	s_add_u32 s8, s8, 0x2000
	s_addc_u32 s9, s9, 0
	global_load_dwordx4 v[176:179], v202, s[8:9]
	s_add_u32 s8, s8, 0x2000
	s_addc_u32 s9, s9, 0
	global_load_dwordx4 v[184:187], v202, s[8:9]
	s_add_u32 s8, s8, 0x2000
	s_addc_u32 s9, s9, 0
	global_load_dwordx4 v[188:191], v202, s[8:9]
	s_add_u32 s8, s8, 0x2000
	s_addc_u32 s9, s9, 0
	s_waitcnt vmcnt(0)
	v_pk_add_f32 v[38:39], v[38:39], v[156:157]
	v_pk_add_f32 v[40:41], v[40:41], v[158:159]
	v_pk_add_f32 v[42:43], v[42:43], v[160:161]
	v_pk_add_f32 v[44:45], v[44:45], v[162:163]
	v_pk_add_f32 v[50:51], v[50:51], v[164:165]
	v_pk_add_f32 v[52:53], v[52:53], v[166:167]
	v_pk_add_f32 v[58:59], v[58:59], v[168:169]
	v_pk_add_f32 v[60:61], v[60:61], v[170:171]
	v_pk_add_f32 v[66:67], v[66:67], v[172:173]
	v_pk_add_f32 v[68:69], v[68:69], v[174:175]
	v_pk_add_f32 v[70:71], v[70:71], v[176:177]
	v_pk_add_f32 v[72:73], v[72:73], v[178:179]
	v_pk_add_f32 v[74:75], v[74:75], v[184:185]
	v_pk_add_f32 v[76:77], v[76:77], v[186:187]
	v_pk_add_f32 v[78:79], v[78:79], v[188:189]
	v_pk_add_f32 v[80:81], v[80:81], v[190:191]
	global_load_dwordx4 v[156:159], v202, s[8:9]
	s_add_u32 s8, s8, 0x2000
	s_addc_u32 s9, s9, 0
	global_load_dwordx4 v[160:163], v202, s[8:9]
	s_add_u32 s8, s8, 0x2000
	s_addc_u32 s9, s9, 0
	global_load_dwordx4 v[164:167], v202, s[8:9]
	s_add_u32 s8, s8, 0x2000
	s_addc_u32 s9, s9, 0
	global_load_dwordx4 v[168:171], v202, s[8:9]
	s_add_u32 s8, s8, 0x2000
	s_addc_u32 s9, s9, 0
	global_load_dwordx4 v[172:175], v202, s[8:9]
	s_add_u32 s8, s8, 0x2000
	s_addc_u32 s9, s9, 0
	global_load_dwordx4 v[176:179], v202, s[8:9]
	s_add_u32 s8, s8, 0x2000
	s_addc_u32 s9, s9, 0
	global_load_dwordx4 v[184:187], v202, s[8:9]
	s_add_u32 s8, s8, 0x2000
	s_addc_u32 s9, s9, 0
	global_load_dwordx4 v[188:191], v202, s[8:9]
	s_add_u32 s8, s8, 0x2000
	s_addc_u32 s9, s9, 0
	s_waitcnt vmcnt(0)
	v_pk_add_f32 v[82:83], v[82:83], v[156:157]
	v_pk_add_f32 v[84:85], v[84:85], v[158:159]
	v_pk_add_f32 v[86:87], v[86:87], v[160:161]
	v_pk_add_f32 v[88:89], v[88:89], v[162:163]
	v_pk_add_f32 v[90:91], v[90:91], v[164:165]
	v_pk_add_f32 v[92:93], v[92:93], v[166:167]
	v_pk_add_f32 v[94:95], v[94:95], v[168:169]
	v_pk_add_f32 v[96:97], v[96:97], v[170:171]
	v_pk_add_f32 v[98:99], v[98:99], v[172:173]
	v_pk_add_f32 v[100:101], v[100:101], v[174:175]
	v_pk_add_f32 v[102:103], v[102:103], v[176:177]
	v_pk_add_f32 v[104:105], v[104:105], v[178:179]
	v_pk_add_f32 v[106:107], v[106:107], v[184:185]
	v_pk_add_f32 v[108:109], v[108:109], v[186:187]
	v_pk_add_f32 v[110:111], v[110:111], v[188:189]
	v_pk_add_f32 v[112:113], v[112:113], v[190:191]
	global_load_dwordx4 v[156:159], v202, s[8:9]
	s_add_u32 s8, s8, 0x2000
	s_addc_u32 s9, s9, 0
	global_load_dwordx4 v[160:163], v202, s[8:9]
	s_add_u32 s8, s8, 0x2000
	s_addc_u32 s9, s9, 0
	global_load_dwordx4 v[164:167], v202, s[8:9]
	s_add_u32 s8, s8, 0x2000
	s_addc_u32 s9, s9, 0
	global_load_dwordx4 v[168:171], v202, s[8:9]
	s_add_u32 s8, s8, 0x2000
	s_addc_u32 s9, s9, 0
	global_load_dwordx4 v[172:175], v202, s[8:9]
	s_add_u32 s8, s8, 0x2000
	s_addc_u32 s9, s9, 0
	global_load_dwordx4 v[176:179], v202, s[8:9]
	s_add_u32 s8, s8, 0x2000
	s_addc_u32 s9, s9, 0
	global_load_dwordx4 v[184:187], v202, s[8:9]
	s_add_u32 s8, s8, 0x2000
	s_addc_u32 s9, s9, 0
	global_load_dwordx4 v[188:191], v202, s[8:9]
	s_add_u32 s8, s8, 0x2000
	s_addc_u32 s9, s9, 0
	s_waitcnt vmcnt(0)
	v_pk_add_f32 v[114:115], v[114:115], v[156:157]
	v_pk_add_f32 v[116:117], v[116:117], v[158:159]
	v_pk_add_f32 v[118:119], v[118:119], v[160:161]
	v_pk_add_f32 v[120:121], v[120:121], v[162:163]
	v_pk_add_f32 v[122:123], v[122:123], v[164:165]
	v_pk_add_f32 v[124:125], v[124:125], v[166:167]
	v_pk_add_f32 v[126:127], v[126:127], v[168:169]
	v_pk_add_f32 v[128:129], v[128:129], v[170:171]
	v_pk_add_f32 v[130:131], v[130:131], v[172:173]
	v_pk_add_f32 v[132:133], v[132:133], v[174:175]
	v_pk_add_f32 v[134:135], v[134:135], v[176:177]
	v_pk_add_f32 v[136:137], v[136:137], v[178:179]
	v_pk_add_f32 v[138:139], v[138:139], v[184:185]
	v_pk_add_f32 v[140:141], v[140:141], v[186:187]
	v_pk_add_f32 v[142:143], v[142:143], v[188:189]
	v_pk_add_f32 v[144:145], v[144:145], v[190:191]
